# retention mixer stage 1: all operand fragment reads issued up front, U MFMAs overlap the P mask/convert
# speedup vs baseline: 1.0077x; 1.0077x over previous
; template <int DK, bool IS_A, int NDV>
; __device__ __forceinline__ void mix_stream(const Params& p, LAS unsigned char* lds, int l, int rs, int T, int h, int dir, int dvh) {
;     ...
;         { const int tt = w >> 1, ts0 = (w & 1) * 2; f32x4 pa = (f32x4){0.f, 0.f, 0.f, 0.f}, pb = pa;
;           bf16x8 gq_[KS], gk0[KS], gk1[KS];
; #pragma unroll
;           for (int ks = 0; ks < KS; ++ks) { gq_[ks] = ldfrag(Qs, QP, tt, ks, fr, fqx); gk0[ks] = ldfrag(Ks, QP, ts0, ks, fr, fqx); gk1[ks] = ldfrag(Ks, QP, ts0 + 1, ks, fr, fqx); }
;           __builtin_amdgcn_sched_barrier(0);
; #pragma unroll
;           for (int ks = 0; ks < KS; ++ks) { pa = MFMA16(gk0[ks], gq_[ks], pa); pb = MFMA16(gk1[ks], gq_[ks], pb); }
;           const int t = tt * 16 + fr, s0 = ts0 * 16 + fq * 4, s1 = s0 + 16;
;           u32x2 w0, w1;
;           w0.x = cvt_pk_bf16(t >= s0 ? pa[0] : 0.f, t >= s0 + 1 ? pa[1] : 0.f); w0.y = cvt_pk_bf16(t >= s0 + 2 ? pa[2] : 0.f, t >= s0 + 3 ? pa[3] : 0.f);
;           w1.x = cvt_pk_bf16(t >= s1 ? pb[0] : 0.f, t >= s1 + 1 ? pb[1] : 0.f); w1.y = cvt_pk_bf16(t >= s1 + 2 ? pb[2] : 0.f, t >= s1 + 3 ? pb[3] : 0.f);
;           *(LAS u32x2*)(Ps + t * TP + ((s0 * 2) ^ (gx << 4))) = w0; *(LAS u32x2*)(Ps + t * TP + ((s1 * 2) ^ (gx << 4))) = w1; }
; #pragma unroll
;         for (int ks = 0; ks < 2; ++ks) { bf16x8 ak[2], bv[DVW];
; #pragma unroll
;             for (int dki = 0; dki < 2; ++dki) ak[dki] = ldfrag(Kt, TP, tdk0 + dki, ks, fr, fqx);
; #pragma unroll
;             for (int dvi = 0; dvi < DVW; ++dvi) bv[dvi] = ldfrag(Vt, TP, tdv0 + dvi, ks, fr, fqx);
;             __builtin_amdgcn_sched_barrier(0);
; #pragma unroll
;             for (int dki = 0; dki < 2; ++dki)
; #pragma unroll
;                 for (int dvi = 0; dvi < DVW; ++dvi) U[dki * DVW + dvi] = MFMA16(ak[dki], bv[dvi], U[dki * DVW + dvi]);
;             __builtin_amdgcn_sched_barrier(0); }
;     ...
;         { const int tp = w >> 2, dp = w & 3; f32x4 o[4];
; #pragma unroll
;           for (int q = 0; q < 4; ++q) o[q] = (f32x4){0.f, 0.f, 0.f, 0.f};
; #pragma unroll
;           for (int kb = 0; kb < KS; kb += 2) { bf16x8 b[2][2], a[2][2];
; #pragma unroll
;               for (int k2 = 0; k2 < 2; ++k2)
; #pragma unroll
;                   for (int i2 = 0; i2 < 2; ++i2) { b[k2][i2] = ldfrag(Qs, QP, 2 * tp + i2, kb + k2, fr, fqx); a[k2][i2] = ldfrag(St, QP, 2 * dp + i2, kb + k2, fr, fqx); }
.LBB0_164:
	s_waitcnt lgkmcnt(0)
	s_barrier
	ds_read_b128 v[106:109], v85
	ds_read_b128 v[110:113], v85 offset:64
	ds_read_b128 v[114:117], v86 offset:9216
	ds_read_b128 v[118:121], v86 offset:9280
	ds_read_b128 v[122:125], v87 offset:9216
	ds_read_b128 v[126:129], v87 offset:9280
	ds_read_b128 v[180:183], v102 offset:36864
	ds_read_b128 v[184:187], v103 offset:36864
	ds_read_b128 v[188:191], v95 offset:18432
	ds_read_b128 v[192:195], v95 offset:20736
	ds_read_b128 v[196:199], v102 offset:36928
	ds_read_b128 v[200:203], v103 offset:36928
	ds_read_b128 v[204:207], v95 offset:18496
	ds_read_b128 v[208:211], v95 offset:20800
	s_waitcnt lgkmcnt(11)
	v_mfma_f32_16x16x32_bf16 v[212:215], v[114:117], v[106:109], 0
	s_waitcnt lgkmcnt(9)
	v_mfma_f32_16x16x32_bf16 v[216:219], v[122:125], v[106:109], 0
	v_mfma_f32_16x16x32_bf16 v[212:215], v[118:121], v[110:113], v[212:215]
	s_waitcnt lgkmcnt(8)
	v_mfma_f32_16x16x32_bf16 v[216:219], v[126:129], v[110:113], v[216:219]
	s_waitcnt lgkmcnt(5)
	v_mfma_f32_16x16x32_bf16 v[122:125], v[180:183], v[188:191], 0
	s_waitcnt lgkmcnt(4)
	v_mfma_f32_16x16x32_bf16 v[106:109], v[180:183], v[192:195], 0
	v_mfma_f32_16x16x32_bf16 v[114:117], v[184:187], v[188:191], 0
	v_mfma_f32_16x16x32_bf16 v[110:113], v[184:187], v[192:195], 0
	s_waitcnt lgkmcnt(1)
	v_mfma_f32_16x16x32_bf16 v[122:125], v[196:199], v[204:207], v[122:125]
	s_waitcnt lgkmcnt(0)
	v_mfma_f32_16x16x32_bf16 v[106:109], v[196:199], v[208:211], v[106:109]
	v_mfma_f32_16x16x32_bf16 v[114:117], v[200:203], v[204:207], v[114:117]
	v_mfma_f32_16x16x32_bf16 v[110:113], v[200:203], v[208:211], v[110:113]
	v_cndmask_b32_e64 v39, v212, 0, s[42:43]
	v_cndmask_b32_e64 v105, 0, v213, s[44:45]
	v_cvt_pk_bf16_f32 v220, v39, v105
	v_cndmask_b32_e64 v39, v214, 0, s[46:47]
	v_cndmask_b32_e64 v105, v215, 0, s[48:49]
	v_cvt_pk_bf16_f32 v221, v39, v105
	v_cndmask_b32_e64 v39, v216, 0, s[50:51]
	v_cndmask_b32_e64 v105, v217, 0, s[52:53]
	v_cvt_pk_bf16_f32 v222, v39, v105
	v_cndmask_b32_e64 v39, v218, 0, s[54:55]
	v_cndmask_b32_e64 v105, v219, 0, s[56:57]
	v_cvt_pk_bf16_f32 v223, v39, v105
	ds_write_b64 v93, v[220:221] offset:64512
	ds_write_b64 v94, v[222:223] offset:64512
	s_waitcnt lgkmcnt(0)
	s_barrier
	ds_read_b128 v[118:121], v97
	ds_read_b128 v[126:129], v97 offset:64
	ds_read_b128 v[130:133], v104 offset:46080
	ds_read_b128 v[134:137], v104 offset:46144
	ds_read_b128 v[138:141], v97 offset:2304
	ds_read_b128 v[142:145], v97 offset:2368
	ds_read_b128 v[146:149], v104 offset:48384
	ds_read_b128 v[150:153], v104 offset:48448
	s_waitcnt lgkmcnt(5)
	v_mfma_f32_16x16x32_bf16 v[154:157], v[130:133], v[118:121], 0
	s_waitcnt lgkmcnt(1)
	v_mfma_f32_16x16x32_bf16 v[118:121], v[146:149], v[118:121], 0
	v_mfma_f32_16x16x32_bf16 v[130:133], v[130:133], v[138:141], 0
	v_mfma_f32_16x16x32_bf16 v[138:141], v[146:149], v[138:141], 0
	v_mfma_f32_16x16x32_bf16 v[146:149], v[134:137], v[126:129], v[154:157]
	s_waitcnt lgkmcnt(0)
	v_mfma_f32_16x16x32_bf16 v[118:121], v[150:153], v[126:129], v[118:121]
	v_mfma_f32_16x16x32_bf16 v[126:129], v[134:137], v[142:145], v[130:133]
	v_mfma_f32_16x16x32_bf16 v[130:133], v[150:153], v[142:145], v[138:141]
	ds_read_b128 v[134:137], v97 offset:64512
	s_nop 1
	ds_read_b128 v[138:141], v97 offset:64576
	ds_read_b128 v[142:145], v104 offset:18432
	ds_read_b128 v[150:153], v104 offset:18496
	ds_read_b128 v[154:157], v98 offset:64512
	ds_read_b128 v[158:161], v98 offset:64576
	ds_read_b128 v[162:165], v104 offset:20736
	ds_read_b128 v[166:169], v104 offset:20800
	s_waitcnt lgkmcnt(5)
	v_mfma_f32_16x16x32_bf16 v[146:149], v[142:145], v[134:137], v[146:149]
	s_waitcnt lgkmcnt(1)
	v_mfma_f32_16x16x32_bf16 v[118:121], v[162:165], v[134:137], v[118:121]
	v_mfma_f32_16x16x32_bf16 v[126:129], v[142:145], v[154:157], v[126:129]
	v_mfma_f32_16x16x32_bf16 v[130:133], v[162:165], v[154:157], v[130:133]
	v_mfma_f32_16x16x32_bf16 v[134:137], v[150:153], v[138:141], v[146:149]
	s_waitcnt lgkmcnt(0)
	v_mfma_f32_16x16x32_bf16 v[118:121], v[166:169], v[138:141], v[118:121]
	v_mfma_f32_16x16x32_bf16 v[126:129], v[150:153], v[158:161], v[126:129]
	v_mfma_f32_16x16x32_bf16 v[130:133], v[166:169], v[158:161], v[130:133]
	v_cvt_pk_bf16_f32 v118, v118, v119
	v_cvt_pk_bf16_f32 v119, v120, v121
	v_mov_b32_e32 v39, v38
	v_pk_mul_f32 v[108:109], v[34:35], v[108:109]
	v_pk_mul_f32 v[106:107], v[36:37], v[106:107]
	v_cvt_pk_bf16_f32 v134, v134, v135
	v_cvt_pk_bf16_f32 v135, v136, v137
	s_nop 2
	ds_write2_b64 v99, v[134:135], v[118:119] offset1:4
	v_cvt_pk_bf16_f32 v118, v126, v127
	v_cvt_pk_bf16_f32 v119, v128, v129
	v_cvt_pk_bf16_f32 v120, v130, v131
	v_cvt_pk_bf16_f32 v121, v132, v133
	v_pk_fma_f32 v[50:51], v[38:39], v[50:51], v[108:109]
	v_pk_fma_f32 v[52:53], v[40:41], v[52:53], v[106:107]
	v_pk_mul_f32 v[106:107], v[34:35], v[116:117]
	v_pk_mul_f32 v[108:109], v[36:37], v[114:115]
	ds_write2_b64 v100, v[118:119], v[120:121] offset1:4
	v_pk_mul_f32 v[118:119], v[34:35], v[124:125]
	v_pk_mul_f32 v[120:121], v[36:37], v[122:123]
	v_pk_fma_f32 v[46:47], v[38:39], v[46:47], v[106:107]
	v_pk_fma_f32 v[48:49], v[40:41], v[48:49], v[108:109]
	v_pk_mul_f32 v[106:107], v[34:35], v[112:113]
	v_pk_mul_f32 v[108:109], v[36:37], v[110:111]
	s_add_i32 s14, s14, 64
	s_sub_i32 s11, s11, 64
	v_pk_fma_f32 v[54:55], v[38:39], v[54:55], v[118:119]
	v_pk_fma_f32 v[56:57], v[40:41], v[56:57], v[120:121]
	v_pk_fma_f32 v[42:43], v[38:39], v[42:43], v[106:107]
	s_cmp_lg_u32 s10, s8
	v_pk_fma_f32 v[44:45], v[40:41], v[44:45], v[108:109]
	s_cbranch_scc0 .LBB0_169

; #define PG8_STAGE(bufoff, gbase, voff) do { _Pragma("unroll") for (int _i = 0; _i < 2; ++_i) \
;         __builtin_amdgcn_global_load_lds((const unsigned*)((const char*)(gbase) + (voff)[_i]), (LAS unsigned*)(lds + (bufoff) + ldsw + _i * 8192), 16, 0, 0); } while (0)
; #define PG8_LDA(dst, b, h) do { _Pragma("unroll") for (int m = 0; m < 4; ++m) _Pragma("unroll") for (int k = 0; k < 2; ++k) dst[m][k] = *(const LAS bf16x8*)(lds + PG8_SA(b, h) + aoff + m * 2048 + k * 1024); } while (0)
; #define PG8_LDB(dst, b, h) do { _Pragma("unroll") for (int n = 0; n < 2; ++n) _Pragma("unroll") for (int k = 0; k < 2; ++k) dst[n][k] = *(const LAS bf16x8*)(lds + PG8_SB(b, h) + boff + n * 2048 + k * 1024); } while (0)
; #define PG8_WAIT_V(n) asm volatile("s_waitcnt vmcnt(" #n ")" ::: "memory")
; #define PG8_WAIT_L(n) asm volatile("s_waitcnt lgkmcnt(" #n ")" ::: "memory")
; #define PG8_BAR __builtin_amdgcn_s_barrier()
; template <class Epi>
; __device__ __forceinline__ void gemm_phase(LAS unsigned char* lds, const Gemm g, const StaticOrder& S, const Epi& E) {
;     ...
;         for (int t = 0; t < nt; t += 2) {
;             const bool last = (t == nt - 2);
;             const char* a1 = cA + (size_t)(t + 1) * kstep;
;             const char* a2 = last ? nA : cA + (size_t)(t + 2) * kstep; const char* b2 = last ? nB : cB + (size_t)(t + 2) * kstep;
;             const char* a3 = a2 + kstep; const char* b3 = b2 + kstep;
;             PG8_LDB(B0, 0, 0); PG8_SCHED; PG8_LDA(At, 0, 0); PG8_STAGE(PG8_SA(1, 1), a1 + hstepA, voffA);
;             PG8_WAIT_L(8); PG8_BAR; PG8_WAIT_L(0); PG8_MMA(0, 0, At, B0); PG8_BAR; PG8_SCHED;
;             PG8_LDB(B1, 0, 1); PG8_STAGE(PG8_SB(0, 0), b2, voffB);
;             PG8_BAR; PG8_WAIT_L(0); PG8_MMA(0, 1, At, B1); PG8_BAR;
;             PG8_LDA(At, 0, 1); PG8_STAGE(PG8_SA(0, 0), a2, voffA);
;             PG8_BAR; PG8_WAIT_L(0); PG8_MMA(1, 0, At, B0); PG8_BAR; PG8_SCHED;
;             PG8_STAGE(PG8_SB(0, 1), b2 + hstepB, voffB);
;             PG8_WAIT_V(6); PG8_BAR; PG8_MMA(1, 1, At, B1); PG8_BAR;
;             PG8_LDB(B0, 1, 0); PG8_SCHED; PG8_LDA(At, 1, 0); PG8_STAGE(PG8_SA(0, 1), a2 + hstepA, voffA);
;             PG8_WAIT_L(8); PG8_BAR; PG8_WAIT_L(0); PG8_MMA(0, 0, At, B0); PG8_BAR; PG8_SCHED;
;             PG8_LDB(B1, 1, 1); PG8_STAGE(PG8_SB(1, 0), b3, voffB);
;             PG8_BAR; PG8_WAIT_L(0); PG8_MMA(0, 1, At, B1); PG8_BAR;
.LBB0_302:
	s_add_u32 s10, s46, s64
	s_addc_u32 s11, s47, s65
	s_add_u32 s100, s10, 0x80
	s_addc_u32 s101, s11, 0
	s_add_u32 s10, s10, 0x100
	s_addc_u32 s11, s11, 0
	s_add_u32 s66, vcc_lo, s64
	s_addc_u32 s67, vcc_hi, s65
	s_add_i32 s72, 0, 0x10000
	v_add_u32_e32 v144, s72, v252
	ds_read_b128 v[132:135], v144
	ds_read_b128 v[136:139], v144 offset:1024
	ds_read_b128 v[140:143], v144 offset:2048
	ds_read_b128 v[144:147], v144 offset:3072
	s_cmpk_eq_i32 s64, 0x700
	s_cselect_b32 s69, s61, s11
	s_cselect_b32 s68, s60, s10
	s_cselect_b32 s67, s59, s67
	s_cselect_b32 s66, s58, s66
	s_add_i32 m0, s12, 0xc000
	ds_read_b128 v[148:151], v241
	ds_read_b128 v[152:155], v241 offset:1024
	ds_read_b128 v[156:159], v241 offset:2048
	ds_read_b128 v[160:163], v241 offset:3072
	ds_read_b128 v[164:167], v241 offset:4096
	ds_read_b128 v[168:171], v241 offset:5120
	ds_read_b128 v[172:175], v241 offset:6144
	ds_read_b128 v[192:195], v241 offset:7168
	global_load_lds_dwordx4 v190, s[100:101]
	s_add_i32 m0, s12, 0xe000
	s_nop 0
	global_load_lds_dwordx4 v188, s[100:101]
	s_waitcnt lgkmcnt(8)
	s_barrier
	s_waitcnt lgkmcnt(0)
	s_setprio 1
	s_waitcnt lgkmcnt(0)
	v_mfma_f32_16x16x32_bf16 v[124:127], v[132:135], v[148:151], v[124:127]
	v_mfma_f32_16x16x32_bf16 v[120:123], v[140:143], v[148:151], v[120:123]
	v_mfma_f32_16x16x32_bf16 v[116:119], v[132:135], v[156:159], v[116:119]
	v_mfma_f32_16x16x32_bf16 v[112:115], v[140:143], v[156:159], v[112:115]
	v_mfma_f32_16x16x32_bf16 v[108:111], v[132:135], v[164:167], v[108:111]
	v_mfma_f32_16x16x32_bf16 v[104:107], v[140:143], v[164:167], v[104:107]
	v_mfma_f32_16x16x32_bf16 v[100:103], v[132:135], v[172:175], v[100:103]
	v_mfma_f32_16x16x32_bf16 v[96:99], v[140:143], v[172:175], v[96:99]
	v_mfma_f32_16x16x32_bf16 v[124:127], v[136:139], v[152:155], v[124:127]
	v_mfma_f32_16x16x32_bf16 v[120:123], v[144:147], v[152:155], v[120:123]
	v_mfma_f32_16x16x32_bf16 v[116:119], v[136:139], v[160:163], v[116:119]
	v_mfma_f32_16x16x32_bf16 v[112:115], v[144:147], v[160:163], v[112:115]
	v_mfma_f32_16x16x32_bf16 v[108:111], v[136:139], v[168:171], v[108:111]
	v_mfma_f32_16x16x32_bf16 v[104:107], v[144:147], v[168:171], v[104:107]
	v_mfma_f32_16x16x32_bf16 v[100:103], v[136:139], v[192:195], v[100:103]
	v_mfma_f32_16x16x32_bf16 v[96:99], v[144:147], v[192:195], v[96:99]
	s_setprio 0
	s_barrier
	s_add_i32 s40, 0, 0x14000
	s_add_i32 s10, s72, s57
	v_add_u32_e32 v176, s40, v252
	s_mov_b32 m0, s10
	ds_read_b128 v[196:199], v176
	ds_read_b128 v[200:203], v176 offset:1024
	ds_read_b128 v[204:207], v176 offset:2048
	ds_read_b128 v[208:211], v176 offset:3072
	global_load_lds_dwordx4 v182, s[66:67]
	s_add_i32 m0, s10, 0x2000
	s_nop 0
	global_load_lds_dwordx4 v186, s[66:67]
	s_barrier
	s_waitcnt lgkmcnt(0)
	s_setprio 1
	s_waitcnt lgkmcnt(0)
	v_mfma_f32_16x16x32_bf16 v[60:63], v[196:199], v[148:151], v[60:63]
	v_mfma_f32_16x16x32_bf16 v[56:59], v[204:207], v[148:151], v[56:59]
	v_mfma_f32_16x16x32_bf16 v[52:55], v[196:199], v[156:159], v[52:55]
	v_mfma_f32_16x16x32_bf16 v[48:51], v[204:207], v[156:159], v[48:51]
	v_mfma_f32_16x16x32_bf16 v[44:47], v[196:199], v[164:167], v[44:47]
	v_mfma_f32_16x16x32_bf16 v[40:43], v[204:207], v[164:167], v[40:43]
	v_mfma_f32_16x16x32_bf16 v[36:39], v[196:199], v[172:175], v[36:39]
	v_mfma_f32_16x16x32_bf16 v[32:35], v[204:207], v[172:175], v[32:35]
	v_mfma_f32_16x16x32_bf16 v[60:63], v[200:203], v[152:155], v[60:63]
	v_mfma_f32_16x16x32_bf16 v[56:59], v[208:211], v[152:155], v[56:59]
	v_mfma_f32_16x16x32_bf16 v[52:55], v[200:203], v[160:163], v[52:55]
	v_mfma_f32_16x16x32_bf16 v[48:51], v[208:211], v[160:163], v[48:51]
	v_mfma_f32_16x16x32_bf16 v[44:47], v[200:203], v[168:171], v[44:47]
	v_mfma_f32_16x16x32_bf16 v[40:43], v[208:211], v[168:171], v[40:43]
	v_mfma_f32_16x16x32_bf16 v[36:39], v[200:203], v[192:195], v[36:39]
	v_mfma_f32_16x16x32_bf16 v[32:35], v[208:211], v[192:195], v[32:35]
	s_setprio 0
	s_mov_b32 m0, s12
	s_barrier
	ds_read_b128 v[148:151], v241 offset:16384
	ds_read_b128 v[152:155], v241 offset:17408
	ds_read_b128 v[156:159], v241 offset:18432
	ds_read_b128 v[160:163], v241 offset:19456
	ds_read_b128 v[164:167], v241 offset:20480
	ds_read_b128 v[168:171], v241 offset:21504
	ds_read_b128 v[172:175], v241 offset:22528
	ds_read_b128 v[192:195], v241 offset:23552
	global_load_lds_dwordx4 v180, s[68:69]
	s_mov_b32 m0, s13
	s_nop 0
	global_load_lds_dwordx4 v184, s[68:69]
	s_barrier
	s_waitcnt lgkmcnt(0)
	s_setprio 1
	s_waitcnt lgkmcnt(0)
	v_mfma_f32_16x16x32_bf16 v[92:95], v[132:135], v[148:151], v[92:95]
	v_mfma_f32_16x16x32_bf16 v[88:91], v[140:143], v[148:151], v[88:91]
	v_mfma_f32_16x16x32_bf16 v[84:87], v[132:135], v[156:159], v[84:87]
	v_mfma_f32_16x16x32_bf16 v[80:83], v[140:143], v[156:159], v[80:83]
	v_mfma_f32_16x16x32_bf16 v[76:79], v[132:135], v[164:167], v[76:79]
	v_mfma_f32_16x16x32_bf16 v[72:75], v[140:143], v[164:167], v[72:75]
	v_mfma_f32_16x16x32_bf16 v[68:71], v[132:135], v[172:175], v[68:71]
	v_mfma_f32_16x16x32_bf16 v[64:67], v[140:143], v[172:175], v[64:67]
	v_mfma_f32_16x16x32_bf16 v[92:95], v[136:139], v[152:155], v[92:95]
	v_mfma_f32_16x16x32_bf16 v[88:91], v[144:147], v[152:155], v[88:91]
	v_mfma_f32_16x16x32_bf16 v[84:87], v[136:139], v[160:163], v[84:87]
	v_mfma_f32_16x16x32_bf16 v[80:83], v[144:147], v[160:163], v[80:83]
	v_mfma_f32_16x16x32_bf16 v[76:79], v[136:139], v[168:171], v[76:79]
	v_mfma_f32_16x16x32_bf16 v[72:75], v[144:147], v[168:171], v[72:75]
	v_mfma_f32_16x16x32_bf16 v[68:71], v[136:139], v[192:195], v[68:71]
	v_mfma_f32_16x16x32_bf16 v[64:67], v[144:147], v[192:195], v[64:67]
	s_setprio 0
	s_barrier
; #define PG8_STAGE(bufoff, gbase, voff) do { _Pragma("unroll") for (int _i = 0; _i < 2; ++_i) \
;         __builtin_amdgcn_global_load_lds((const unsigned*)((const char*)(gbase) + (voff)[_i]), (LAS unsigned*)(lds + (bufoff) + ldsw + _i * 8192), 16, 0, 0); } while (0)
; #define PG8_LDA(dst, b, h) do { _Pragma("unroll") for (int m = 0; m < 4; ++m) _Pragma("unroll") for (int k = 0; k < 2; ++k) dst[m][k] = *(const LAS bf16x8*)(lds + PG8_SA(b, h) + aoff + m * 2048 + k * 1024); } while (0)
; #define PG8_LDB(dst, b, h) do { _Pragma("unroll") for (int n = 0; n < 2; ++n) _Pragma("unroll") for (int k = 0; k < 2; ++k) dst[n][k] = *(const LAS bf16x8*)(lds + PG8_SB(b, h) + boff + n * 2048 + k * 1024); } while (0)
; #define PG8_MMA(ai, bj, At, Bt) do { __builtin_amdgcn_s_setprio(1); _Pragma("unroll") for (int m = 0; m < 4; ++m) _Pragma("unroll") for (int n = 0; n < 2; ++n) _Pragma("unroll") for (int k = 0; k < 2; ++k) \
;         acc[ai][bj][m][n] = __builtin_amdgcn_mfma_f32_16x16x32_bf16(Bt[n][k], At[m][k], acc[ai][bj][m][n], 0, 0, 0); __builtin_amdgcn_s_setprio(0); } while (0)
; #define PG8_WAIT_V(n) asm volatile("s_waitcnt vmcnt(" #n ")" ::: "memory")
; #define PG8_WAIT_L(n) asm volatile("s_waitcnt lgkmcnt(" #n ")" ::: "memory")
; #define PG8_BAR __builtin_amdgcn_s_barrier()
; #define PG8_SCHED __builtin_amdgcn_sched_barrier(0)
; template <class Epi>
; __device__ __forceinline__ void gemm_phase(LAS unsigned char* lds, const Gemm g, const StaticOrder& S, const Epi& E) {
;     ...
;             PG8_BAR; PG8_WAIT_L(0); PG8_MMA(1, 0, At, B0); PG8_BAR; PG8_SCHED;
;             PG8_STAGE(PG8_SB(0, 1), b2 + hstepB, voffB);
;             PG8_WAIT_V(6); PG8_BAR; PG8_MMA(1, 1, At, B1); PG8_BAR;
;             PG8_LDB(B0, 1, 0); PG8_SCHED; PG8_LDA(At, 1, 0); PG8_STAGE(PG8_SA(0, 1), a2 + hstepA, voffA);
;             PG8_WAIT_L(8); PG8_BAR; PG8_WAIT_L(0); PG8_MMA(0, 0, At, B0); PG8_BAR; PG8_SCHED;
;             PG8_LDB(B1, 1, 1); PG8_STAGE(PG8_SB(1, 0), b3, voffB);
;             PG8_BAR; PG8_WAIT_L(0); PG8_MMA(0, 1, At, B1); PG8_BAR;
;             PG8_LDA(At, 1, 1); PG8_STAGE(PG8_SA(1, 0), a3, voffA);
;             PG8_BAR; PG8_WAIT_L(0); PG8_MMA(1, 0, At, B0); PG8_BAR; PG8_SCHED;
;             PG8_STAGE(PG8_SB(1, 1), b3 + hstepB, voffB);
;             PG8_WAIT_V(6); PG8_BAR; PG8_MMA(1, 1, At, B1); PG8_BAR;
	s_add_u32 s10, s66, 0x40000
	s_addc_u32 s11, s67, 0
	s_add_i32 s40, s40, s57
	s_mov_b32 m0, s40
	s_nop 0
	global_load_lds_dwordx4 v182, s[10:11]
	s_add_i32 m0, s40, 0x2000
	s_nop 0
	global_load_lds_dwordx4 v186, s[10:11]
	s_waitcnt vmcnt(6)
	s_barrier
	s_setprio 1
	v_mfma_f32_16x16x32_bf16 v[28:31], v[196:199], v[148:151], v[28:31]
	v_mfma_f32_16x16x32_bf16 v[24:27], v[204:207], v[148:151], v[24:27]
	v_mfma_f32_16x16x32_bf16 v[20:23], v[196:199], v[156:159], v[20:23]
	v_mfma_f32_16x16x32_bf16 v[16:19], v[204:207], v[156:159], v[16:19]
	v_mfma_f32_16x16x32_bf16 v[12:15], v[196:199], v[164:167], v[12:15]
	v_mfma_f32_16x16x32_bf16 v[8:11], v[204:207], v[164:167], v[8:11]
	v_mfma_f32_16x16x32_bf16 v[4:7], v[196:199], v[172:175], v[4:7]
	v_mfma_f32_16x16x32_bf16 v[0:3], v[204:207], v[172:175], v[0:3]
	v_mfma_f32_16x16x32_bf16 v[28:31], v[200:203], v[152:155], v[28:31]
	v_mfma_f32_16x16x32_bf16 v[24:27], v[208:211], v[152:155], v[24:27]
	v_mfma_f32_16x16x32_bf16 v[20:23], v[200:203], v[160:163], v[20:23]
	v_mfma_f32_16x16x32_bf16 v[16:19], v[208:211], v[160:163], v[16:19]
	v_mfma_f32_16x16x32_bf16 v[12:15], v[200:203], v[168:171], v[12:15]
	v_mfma_f32_16x16x32_bf16 v[8:11], v[208:211], v[168:171], v[8:11]
	v_mfma_f32_16x16x32_bf16 v[4:7], v[200:203], v[192:195], v[4:7]
	v_mfma_f32_16x16x32_bf16 v[0:3], v[208:211], v[192:195], v[0:3]
	s_setprio 0
	s_add_i32 s40, 0, 0x18000
	v_add_u32_e32 v144, s40, v252
	s_barrier
	ds_read_b128 v[132:135], v144
	ds_read_b128 v[136:139], v144 offset:1024
	ds_read_b128 v[140:143], v144 offset:2048
	ds_read_b128 v[144:147], v144 offset:3072
	s_add_u32 s10, s68, s54
	s_addc_u32 s11, s69, 0
	s_mov_b32 m0, s4
	ds_read_b128 v[148:151], v241 offset:32768
	ds_read_b128 v[152:155], v241 offset:33792
	ds_read_b128 v[156:159], v241 offset:34816
	ds_read_b128 v[160:163], v241 offset:35840
	ds_read_b128 v[164:167], v241 offset:36864
	ds_read_b128 v[168:171], v241 offset:37888
	ds_read_b128 v[172:175], v241 offset:38912
	ds_read_b128 v[192:195], v241 offset:39936
	global_load_lds_dwordx4 v180, s[10:11]
	s_mov_b32 m0, s70
	s_nop 0
	global_load_lds_dwordx4 v184, s[10:11]
	s_waitcnt lgkmcnt(8)
	s_barrier
	s_waitcnt lgkmcnt(0)
	s_setprio 1
	s_waitcnt lgkmcnt(0)
	v_mfma_f32_16x16x32_bf16 v[124:127], v[132:135], v[148:151], v[124:127]
	v_mfma_f32_16x16x32_bf16 v[120:123], v[140:143], v[148:151], v[120:123]
	v_mfma_f32_16x16x32_bf16 v[116:119], v[132:135], v[156:159], v[116:119]
	v_mfma_f32_16x16x32_bf16 v[112:115], v[140:143], v[156:159], v[112:115]
	v_mfma_f32_16x16x32_bf16 v[108:111], v[132:135], v[164:167], v[108:111]
	v_mfma_f32_16x16x32_bf16 v[104:107], v[140:143], v[164:167], v[104:107]
	v_mfma_f32_16x16x32_bf16 v[100:103], v[132:135], v[172:175], v[100:103]
	v_mfma_f32_16x16x32_bf16 v[96:99], v[140:143], v[172:175], v[96:99]
	v_mfma_f32_16x16x32_bf16 v[124:127], v[136:139], v[152:155], v[124:127]
	v_mfma_f32_16x16x32_bf16 v[120:123], v[144:147], v[152:155], v[120:123]
	v_mfma_f32_16x16x32_bf16 v[116:119], v[136:139], v[160:163], v[116:119]
	v_mfma_f32_16x16x32_bf16 v[112:115], v[144:147], v[160:163], v[112:115]
	v_mfma_f32_16x16x32_bf16 v[108:111], v[136:139], v[168:171], v[108:111]
	v_mfma_f32_16x16x32_bf16 v[104:107], v[144:147], v[168:171], v[104:107]
	v_mfma_f32_16x16x32_bf16 v[100:103], v[136:139], v[192:195], v[100:103]
	v_mfma_f32_16x16x32_bf16 v[96:99], v[144:147], v[192:195], v[96:99]
	s_setprio 0
	s_barrier
	s_add_i32 s41, 0, 0x1c000
	s_add_i32 s10, s40, s57
	v_add_u32_e32 v176, s41, v252
	s_add_u32 s100, s66, 0x80
	s_addc_u32 s101, s67, 0
	s_mov_b32 m0, s10
	ds_read_b128 v[196:199], v176
	ds_read_b128 v[200:203], v176 offset:1024
	ds_read_b128 v[204:207], v176 offset:2048
	ds_read_b128 v[208:211], v176 offset:3072
	global_load_lds_dwordx4 v182, s[100:101]
	s_add_i32 m0, s10, 0x2000
	s_nop 0
	global_load_lds_dwordx4 v186, s[100:101]
	s_barrier
	s_waitcnt lgkmcnt(0)
	s_setprio 1
	s_waitcnt lgkmcnt(0)
	v_mfma_f32_16x16x32_bf16 v[60:63], v[196:199], v[148:151], v[60:63]
	v_mfma_f32_16x16x32_bf16 v[56:59], v[204:207], v[148:151], v[56:59]
	v_mfma_f32_16x16x32_bf16 v[52:55], v[196:199], v[156:159], v[52:55]
	v_mfma_f32_16x16x32_bf16 v[48:51], v[204:207], v[156:159], v[48:51]
	v_mfma_f32_16x16x32_bf16 v[44:47], v[196:199], v[164:167], v[44:47]
	v_mfma_f32_16x16x32_bf16 v[40:43], v[204:207], v[164:167], v[40:43]
	v_mfma_f32_16x16x32_bf16 v[36:39], v[196:199], v[172:175], v[36:39]
	v_mfma_f32_16x16x32_bf16 v[32:35], v[204:207], v[172:175], v[32:35]
	v_mfma_f32_16x16x32_bf16 v[60:63], v[200:203], v[152:155], v[60:63]
	v_mfma_f32_16x16x32_bf16 v[56:59], v[208:211], v[152:155], v[56:59]
	v_mfma_f32_16x16x32_bf16 v[52:55], v[200:203], v[160:163], v[52:55]
	v_mfma_f32_16x16x32_bf16 v[48:51], v[208:211], v[160:163], v[48:51]
	v_mfma_f32_16x16x32_bf16 v[44:47], v[200:203], v[168:171], v[44:47]
	v_mfma_f32_16x16x32_bf16 v[40:43], v[208:211], v[168:171], v[40:43]
	v_mfma_f32_16x16x32_bf16 v[36:39], v[200:203], v[192:195], v[36:39]
	v_mfma_f32_16x16x32_bf16 v[32:35], v[208:211], v[192:195], v[32:35]
	s_setprio 0
	s_mov_b32 m0, s6
	s_add_u32 s100, s68, 0x80
	s_addc_u32 s101, s69, 0
	s_barrier
	ds_read_b128 v[148:151], v241 offset:49152
	ds_read_b128 v[152:155], v241 offset:50176
	ds_read_b128 v[156:159], v241 offset:51200
	ds_read_b128 v[160:163], v241 offset:52224
	ds_read_b128 v[164:167], v241 offset:53248
	ds_read_b128 v[168:171], v241 offset:54272
	ds_read_b128 v[172:175], v241 offset:55296
	ds_read_b128 v[192:195], v241 offset:56320
	global_load_lds_dwordx4 v180, s[100:101]
	s_mov_b32 m0, s78
	s_nop 0
	global_load_lds_dwordx4 v184, s[100:101]
	s_barrier
; __device__ __forceinline__ float bf_lo(unsigned u) { return __uint_as_float(u << 16); }
; __device__ __forceinline__ float bf_hi(unsigned u) { return __uint_as_float(u & 0xffff0000u); }
; #define PG8_STAGE(bufoff, gbase, voff) do { _Pragma("unroll") for (int _i = 0; _i < 2; ++_i) \
;         __builtin_amdgcn_global_load_lds((const unsigned*)((const char*)(gbase) + (voff)[_i]), (LAS unsigned*)(lds + (bufoff) + ldsw + _i * 8192), 16, 0, 0); } while (0)
; #define PG8_LDA(dst, b, h) do { _Pragma("unroll") for (int m = 0; m < 4; ++m) _Pragma("unroll") for (int k = 0; k < 2; ++k) dst[m][k] = *(const LAS bf16x8*)(lds + PG8_SA(b, h) + aoff + m * 2048 + k * 1024); } while (0)
; #define PG8_WAIT_V(n) asm volatile("s_waitcnt vmcnt(" #n ")" ::: "memory")
; #define PG8_WAIT_L(n) asm volatile("s_waitcnt lgkmcnt(" #n ")" ::: "memory")
; #define PG8_BAR __builtin_amdgcn_s_barrier()
; #define PG8_SCHED __builtin_amdgcn_sched_barrier(0)
; template <class Epi>
; __device__ __forceinline__ void gemm_phase(LAS unsigned char* lds, const Gemm g, const StaticOrder& S, const Epi& E) {
;     ...
;             PG8_LDA(At, 1, 1); PG8_STAGE(PG8_SA(1, 0), a3, voffA);
;             PG8_BAR; PG8_WAIT_L(0); PG8_MMA(1, 0, At, B0); PG8_BAR; PG8_SCHED;
;             PG8_STAGE(PG8_SB(1, 1), b3 + hstepB, voffB);
;             PG8_WAIT_V(6); PG8_BAR; PG8_MMA(1, 1, At, B1); PG8_BAR;
;         }
;         if (!lastpass) { E.mid(acc, cur, wr, wc, fr, fq); cA = nA; cB = nB; }
;     __device__ __forceinline__ void mid(f32x4 (&acc)[2][2][4][2], const pg8::Unit& u, int wr, int wc, int fr_in, int fq_in) const {
;         int fr = fr_in, fq = fq_in; asm volatile("" : "+v"(fr), "+v"(fq));
;         const int row0 = u.pm * 256 + wr * 64 + fr, col0 = u.pn * 256 + wc * 32 + 8 * fq;
; #pragma unroll
;         for (int i = 0; i < 16; ++i) { const int ai = i >> 3, m = (i >> 1) & 3, bj = i & 1; const int n = col0 + bj * 128;
;             const u32x4 gq = *(const u32x4*)(proj + (size_t)(row0 + ai * 128 + m * 16) * NC1 + C_MG + (n >> 7) * 256 + (n & 127));
;             acc[ai][bj][m][0][0] *= bf_lo(gq.x); acc[ai][bj][m][0][1] *= bf_hi(gq.x); acc[ai][bj][m][0][2] *= bf_lo(gq.y); acc[ai][bj][m][0][3] *= bf_hi(gq.y);
;             acc[ai][bj][m][1][0] *= bf_lo(gq.z); acc[ai][bj][m][1][1] *= bf_hi(gq.z); acc[ai][bj][m][1][2] *= bf_lo(gq.w); acc[ai][bj][m][1][3] *= bf_hi(gq.w); }
	s_waitcnt lgkmcnt(0)
	s_setprio 1
	s_waitcnt lgkmcnt(0)
	v_mfma_f32_16x16x32_bf16 v[92:95], v[132:135], v[148:151], v[92:95]
	v_mfma_f32_16x16x32_bf16 v[88:91], v[140:143], v[148:151], v[88:91]
	v_mfma_f32_16x16x32_bf16 v[84:87], v[132:135], v[156:159], v[84:87]
	v_mfma_f32_16x16x32_bf16 v[80:83], v[140:143], v[156:159], v[80:83]
	v_mfma_f32_16x16x32_bf16 v[76:79], v[132:135], v[164:167], v[76:79]
	v_mfma_f32_16x16x32_bf16 v[72:75], v[140:143], v[164:167], v[72:75]
	v_mfma_f32_16x16x32_bf16 v[68:71], v[132:135], v[172:175], v[68:71]
	v_mfma_f32_16x16x32_bf16 v[64:67], v[140:143], v[172:175], v[64:67]
	v_mfma_f32_16x16x32_bf16 v[92:95], v[136:139], v[152:155], v[92:95]
	v_mfma_f32_16x16x32_bf16 v[88:91], v[144:147], v[152:155], v[88:91]
	v_mfma_f32_16x16x32_bf16 v[84:87], v[136:139], v[160:163], v[84:87]
	v_mfma_f32_16x16x32_bf16 v[80:83], v[144:147], v[160:163], v[80:83]
	v_mfma_f32_16x16x32_bf16 v[76:79], v[136:139], v[168:171], v[76:79]
	v_mfma_f32_16x16x32_bf16 v[72:75], v[144:147], v[168:171], v[72:75]
	v_mfma_f32_16x16x32_bf16 v[68:71], v[136:139], v[192:195], v[68:71]
	v_mfma_f32_16x16x32_bf16 v[64:67], v[144:147], v[192:195], v[64:67]
	s_setprio 0
	s_barrier
	s_add_u32 s10, s66, 0x40080
	s_addc_u32 s11, s67, 0
	s_add_i32 s40, s41, s57
	s_mov_b32 m0, s40
	s_nop 0
	global_load_lds_dwordx4 v182, s[10:11]
	s_add_i32 m0, s40, 0x2000
	s_nop 0
	global_load_lds_dwordx4 v186, s[10:11]
	s_waitcnt vmcnt(6)
	s_barrier
	s_setprio 1
	v_mfma_f32_16x16x32_bf16 v[28:31], v[196:199], v[148:151], v[28:31]
	v_mfma_f32_16x16x32_bf16 v[24:27], v[204:207], v[148:151], v[24:27]
	v_mfma_f32_16x16x32_bf16 v[20:23], v[196:199], v[156:159], v[20:23]
	v_mfma_f32_16x16x32_bf16 v[16:19], v[204:207], v[156:159], v[16:19]
	v_mfma_f32_16x16x32_bf16 v[12:15], v[196:199], v[164:167], v[12:15]
	v_mfma_f32_16x16x32_bf16 v[8:11], v[204:207], v[164:167], v[8:11]
	v_mfma_f32_16x16x32_bf16 v[4:7], v[196:199], v[172:175], v[4:7]
	v_mfma_f32_16x16x32_bf16 v[0:3], v[204:207], v[172:175], v[0:3]
	v_mfma_f32_16x16x32_bf16 v[28:31], v[200:203], v[152:155], v[28:31]
	v_mfma_f32_16x16x32_bf16 v[24:27], v[208:211], v[152:155], v[24:27]
	v_mfma_f32_16x16x32_bf16 v[20:23], v[200:203], v[160:163], v[20:23]
	v_mfma_f32_16x16x32_bf16 v[16:19], v[208:211], v[160:163], v[16:19]
	v_mfma_f32_16x16x32_bf16 v[12:15], v[200:203], v[168:171], v[12:15]
	v_mfma_f32_16x16x32_bf16 v[8:11], v[208:211], v[168:171], v[8:11]
	v_mfma_f32_16x16x32_bf16 v[4:7], v[200:203], v[192:195], v[4:7]
	v_mfma_f32_16x16x32_bf16 v[0:3], v[208:211], v[192:195], v[0:3]
	s_setprio 0
	s_add_i32 s77, s77, 2
	s_add_u32 s64, s64, 0x100
	s_addc_u32 s65, s65, 0
	s_cmp_gt_u32 s77, 13
	s_barrier
	s_cbranch_scc0 .LBB0_302
	s_add_u32 s64, vcc_lo, 0xffffff00
	s_addc_u32 s65, vcc_hi, -1
	s_and_b64 vcc, exec, s[62:63]
	s_cbranch_vccz .LBB0_300
	v_mov_b32_e32 v128, v251
	v_mov_b32_e32 v129, v179
	v_mov_b64_e32 v[130:131], s[98:99]
	v_lshl_add_u32 v128, v128, 3, s16
	v_lshlrev_b32_e32 v132, 1, v128
	v_add_u32_e32 v134, s15, v129
	v_and_b32_e32 v140, 0xffffff00, v132
	v_and_b32_e32 v135, 0x78, v128
	v_mad_i64_i32 v[128:129], s[10:11], v134, s22, v[130:131]
	v_ashrrev_i32_e32 v141, 31, v140
	v_lshl_add_u64 v[128:129], v[128:129], 0, s[34:35]
	v_lshlrev_b64 v[132:133], 1, v[140:141]
	v_lshlrev_b32_e32 v176, 1, v135
	v_lshl_add_u64 v[128:129], v[128:129], 0, v[132:133]
	v_lshl_add_u64 v[128:129], v[128:129], 0, v[176:177]
	s_mov_b64 s[64:65], s[44:45]
	s_mov_b64 s[46:47], s[0:1]
	s_mov_b64 s[100:101], 0x50000
	global_load_dwordx4 v[132:135], v[128:129], off
	global_load_dwordx4 v[136:139], v[128:129], off offset:512
	v_lshl_add_u64 v[130:131], v[128:129], 0, s[100:101]
	global_load_dwordx4 v[140:143], v[130:131], off
	global_load_dwordx4 v[144:147], v[130:131], off offset:512
	v_lshl_add_u64 v[130:131], v[130:131], 0, s[100:101]
	global_load_dwordx4 v[148:151], v[130:131], off
	global_load_dwordx4 v[152:155], v[130:131], off offset:512
	v_lshl_add_u64 v[130:131], v[130:131], 0, s[100:101]
	global_load_dwordx4 v[156:159], v[130:131], off
	global_load_dwordx4 v[160:163], v[130:131], off offset:512
	s_mov_b64 s[100:101], 0x280000
	v_lshl_add_u64 v[130:131], v[128:129], 0, s[100:101]
	s_mov_b64 s[100:101], 0x50000
	global_load_dwordx4 v[164:167], v[130:131], off
	global_load_dwordx4 v[168:171], v[130:131], off offset:512
	v_lshl_add_u64 v[130:131], v[130:131], 0, s[100:101]
	global_load_dwordx4 v[172:175], v[130:131], off
	global_load_dwordx4 v[192:195], v[130:131], off offset:512
	v_lshl_add_u64 v[130:131], v[130:131], 0, s[100:101]
	global_load_dwordx4 v[196:199], v[130:131], off
	global_load_dwordx4 v[200:203], v[130:131], off offset:512
	v_lshl_add_u64 v[130:131], v[130:131], 0, s[100:101]
	global_load_dwordx4 v[204:207], v[130:131], off
	global_load_dwordx4 v[208:211], v[130:131], off offset:512
	s_waitcnt vmcnt(15)
	v_lshlrev_b32_e32 v128, 16, v132
	v_and_b32_e32 v129, 0xffff0000, v132
	v_lshlrev_b32_e32 v130, 16, v133
	v_and_b32_e32 v131, 0xffff0000, v133
	v_pk_mul_f32 v[124:125], v[124:125], v[128:129]
	v_pk_mul_f32 v[126:127], v[126:127], v[130:131]
	v_lshlrev_b32_e32 v128, 16, v134
	v_and_b32_e32 v129, 0xffff0000, v134
	v_lshlrev_b32_e32 v130, 16, v135
	v_and_b32_e32 v131, 0xffff0000, v135
	v_pk_mul_f32 v[120:121], v[120:121], v[128:129]
	v_pk_mul_f32 v[122:123], v[122:123], v[130:131]
	s_waitcnt vmcnt(14)
	v_lshlrev_b32_e32 v128, 16, v136
	v_and_b32_e32 v129, 0xffff0000, v136
	v_lshlrev_b32_e32 v130, 16, v137
	v_and_b32_e32 v131, 0xffff0000, v137
	v_pk_mul_f32 v[60:61], v[60:61], v[128:129]
	v_pk_mul_f32 v[62:63], v[62:63], v[130:131]
	v_lshlrev_b32_e32 v128, 16, v138
	v_and_b32_e32 v129, 0xffff0000, v138
	v_lshlrev_b32_e32 v130, 16, v139
	v_and_b32_e32 v131, 0xffff0000, v139
	v_pk_mul_f32 v[56:57], v[56:57], v[128:129]
	v_pk_mul_f32 v[58:59], v[58:59], v[130:131]
	s_waitcnt vmcnt(13)
; __device__ __forceinline__ float bf_lo(unsigned u) { return __uint_as_float(u << 16); }
; __device__ __forceinline__ float bf_hi(unsigned u) { return __uint_as_float(u & 0xffff0000u); }
;     __device__ __forceinline__ void mid(f32x4 (&acc)[2][2][4][2], const pg8::Unit& u, int wr, int wc, int fr_in, int fq_in) const {
;     ...
;         for (int i = 0; i < 16; ++i) { const int ai = i >> 3, m = (i >> 1) & 3, bj = i & 1; const int n = col0 + bj * 128;
;             const u32x4 gq = *(const u32x4*)(proj + (size_t)(row0 + ai * 128 + m * 16) * NC1 + C_MG + (n >> 7) * 256 + (n & 127));
;             acc[ai][bj][m][0][0] *= bf_lo(gq.x); acc[ai][bj][m][0][1] *= bf_hi(gq.x); acc[ai][bj][m][0][2] *= bf_lo(gq.y); acc[ai][bj][m][0][3] *= bf_hi(gq.y);
;             acc[ai][bj][m][1][0] *= bf_lo(gq.z); acc[ai][bj][m][1][1] *= bf_hi(gq.z); acc[ai][bj][m][1][2] *= bf_lo(gq.w); acc[ai][bj][m][1][3] *= bf_hi(gq.w); }
	v_lshlrev_b32_e32 v128, 16, v140
	v_and_b32_e32 v129, 0xffff0000, v140
	v_lshlrev_b32_e32 v130, 16, v141
	v_and_b32_e32 v131, 0xffff0000, v141
	v_pk_mul_f32 v[116:117], v[116:117], v[128:129]
	v_pk_mul_f32 v[118:119], v[118:119], v[130:131]
	v_lshlrev_b32_e32 v128, 16, v142
	v_and_b32_e32 v129, 0xffff0000, v142
	v_lshlrev_b32_e32 v130, 16, v143
	v_and_b32_e32 v131, 0xffff0000, v143
	v_pk_mul_f32 v[112:113], v[112:113], v[128:129]
	v_pk_mul_f32 v[114:115], v[114:115], v[130:131]
	s_waitcnt vmcnt(12)
	v_lshlrev_b32_e32 v128, 16, v144
	v_and_b32_e32 v129, 0xffff0000, v144
	v_lshlrev_b32_e32 v130, 16, v145
	v_and_b32_e32 v131, 0xffff0000, v145
	v_pk_mul_f32 v[52:53], v[52:53], v[128:129]
	v_pk_mul_f32 v[54:55], v[54:55], v[130:131]
	v_lshlrev_b32_e32 v128, 16, v146
	v_and_b32_e32 v129, 0xffff0000, v146
	v_lshlrev_b32_e32 v130, 16, v147
	v_and_b32_e32 v131, 0xffff0000, v147
	v_pk_mul_f32 v[48:49], v[48:49], v[128:129]
	v_pk_mul_f32 v[50:51], v[50:51], v[130:131]
	s_waitcnt vmcnt(11)
	v_lshlrev_b32_e32 v128, 16, v148
	v_and_b32_e32 v129, 0xffff0000, v148
	v_lshlrev_b32_e32 v130, 16, v149
	v_and_b32_e32 v131, 0xffff0000, v149
	v_pk_mul_f32 v[108:109], v[108:109], v[128:129]
	v_pk_mul_f32 v[110:111], v[110:111], v[130:131]
	v_lshlrev_b32_e32 v128, 16, v150
	v_and_b32_e32 v129, 0xffff0000, v150
	v_lshlrev_b32_e32 v130, 16, v151
	v_and_b32_e32 v131, 0xffff0000, v151
	v_pk_mul_f32 v[104:105], v[104:105], v[128:129]
	v_pk_mul_f32 v[106:107], v[106:107], v[130:131]
	s_waitcnt vmcnt(10)
	v_lshlrev_b32_e32 v128, 16, v152
	v_and_b32_e32 v129, 0xffff0000, v152
	v_lshlrev_b32_e32 v130, 16, v153
	v_and_b32_e32 v131, 0xffff0000, v153
	v_pk_mul_f32 v[44:45], v[44:45], v[128:129]
	v_pk_mul_f32 v[46:47], v[46:47], v[130:131]
	v_lshlrev_b32_e32 v128, 16, v154
	v_and_b32_e32 v129, 0xffff0000, v154
	v_lshlrev_b32_e32 v130, 16, v155
	v_and_b32_e32 v131, 0xffff0000, v155
	v_pk_mul_f32 v[40:41], v[40:41], v[128:129]
	v_pk_mul_f32 v[42:43], v[42:43], v[130:131]
	s_waitcnt vmcnt(9)
	v_lshlrev_b32_e32 v128, 16, v156
	v_and_b32_e32 v129, 0xffff0000, v156
	v_lshlrev_b32_e32 v130, 16, v157
	v_and_b32_e32 v131, 0xffff0000, v157
	v_pk_mul_f32 v[100:101], v[100:101], v[128:129]
	v_pk_mul_f32 v[102:103], v[102:103], v[130:131]
	v_lshlrev_b32_e32 v128, 16, v158
	v_and_b32_e32 v129, 0xffff0000, v158
	v_lshlrev_b32_e32 v130, 16, v159
	v_and_b32_e32 v131, 0xffff0000, v159
	v_pk_mul_f32 v[96:97], v[96:97], v[128:129]
	v_pk_mul_f32 v[98:99], v[98:99], v[130:131]
	s_waitcnt vmcnt(8)
	v_lshlrev_b32_e32 v128, 16, v160
	v_and_b32_e32 v129, 0xffff0000, v160
	v_lshlrev_b32_e32 v130, 16, v161
	v_and_b32_e32 v131, 0xffff0000, v161
	v_pk_mul_f32 v[36:37], v[36:37], v[128:129]
	v_pk_mul_f32 v[38:39], v[38:39], v[130:131]
	v_lshlrev_b32_e32 v128, 16, v162
	v_and_b32_e32 v129, 0xffff0000, v162
	v_lshlrev_b32_e32 v130, 16, v163
	v_and_b32_e32 v131, 0xffff0000, v163
	v_pk_mul_f32 v[32:33], v[32:33], v[128:129]
	v_pk_mul_f32 v[34:35], v[34:35], v[130:131]
	s_waitcnt vmcnt(7)
	v_lshlrev_b32_e32 v128, 16, v164
	v_and_b32_e32 v129, 0xffff0000, v164
	v_lshlrev_b32_e32 v130, 16, v165
	v_and_b32_e32 v131, 0xffff0000, v165
	v_pk_mul_f32 v[92:93], v[92:93], v[128:129]
	v_pk_mul_f32 v[94:95], v[94:95], v[130:131]
	v_lshlrev_b32_e32 v128, 16, v166
	v_and_b32_e32 v129, 0xffff0000, v166
	v_lshlrev_b32_e32 v130, 16, v167
	v_and_b32_e32 v131, 0xffff0000, v167
	v_pk_mul_f32 v[88:89], v[88:89], v[128:129]
	v_pk_mul_f32 v[90:91], v[90:91], v[130:131]
	s_waitcnt vmcnt(6)
	v_lshlrev_b32_e32 v128, 16, v168
	v_and_b32_e32 v129, 0xffff0000, v168
	v_lshlrev_b32_e32 v130, 16, v169
	v_and_b32_e32 v131, 0xffff0000, v169
	v_pk_mul_f32 v[28:29], v[28:29], v[128:129]
	v_pk_mul_f32 v[30:31], v[30:31], v[130:131]
	v_lshlrev_b32_e32 v128, 16, v170
	v_and_b32_e32 v129, 0xffff0000, v170
	v_lshlrev_b32_e32 v130, 16, v171
	v_and_b32_e32 v131, 0xffff0000, v171
	v_pk_mul_f32 v[24:25], v[24:25], v[128:129]
	v_pk_mul_f32 v[26:27], v[26:27], v[130:131]
	s_waitcnt vmcnt(5)
	v_lshlrev_b32_e32 v128, 16, v172
	v_and_b32_e32 v129, 0xffff0000, v172
	v_lshlrev_b32_e32 v130, 16, v173
	v_and_b32_e32 v131, 0xffff0000, v173
	v_pk_mul_f32 v[84:85], v[84:85], v[128:129]
	v_pk_mul_f32 v[86:87], v[86:87], v[130:131]
	v_lshlrev_b32_e32 v128, 16, v174
	v_and_b32_e32 v129, 0xffff0000, v174
	v_lshlrev_b32_e32 v130, 16, v175
	v_and_b32_e32 v131, 0xffff0000, v175
	v_pk_mul_f32 v[80:81], v[80:81], v[128:129]
	v_pk_mul_f32 v[82:83], v[82:83], v[130:131]
	s_waitcnt vmcnt(4)
	v_lshlrev_b32_e32 v128, 16, v192
	v_and_b32_e32 v129, 0xffff0000, v192
	v_lshlrev_b32_e32 v130, 16, v193
	v_and_b32_e32 v131, 0xffff0000, v193
	v_pk_mul_f32 v[20:21], v[20:21], v[128:129]
	v_pk_mul_f32 v[22:23], v[22:23], v[130:131]
	v_lshlrev_b32_e32 v128, 16, v194
	v_and_b32_e32 v129, 0xffff0000, v194
	v_lshlrev_b32_e32 v130, 16, v195
	v_and_b32_e32 v131, 0xffff0000, v195
	v_pk_mul_f32 v[16:17], v[16:17], v[128:129]
	v_pk_mul_f32 v[18:19], v[18:19], v[130:131]
	s_waitcnt vmcnt(3)
	v_lshlrev_b32_e32 v128, 16, v196
	v_and_b32_e32 v129, 0xffff0000, v196
	v_lshlrev_b32_e32 v130, 16, v197
	v_and_b32_e32 v131, 0xffff0000, v197
	v_pk_mul_f32 v[76:77], v[76:77], v[128:129]
	v_pk_mul_f32 v[78:79], v[78:79], v[130:131]
	v_lshlrev_b32_e32 v128, 16, v198
	v_and_b32_e32 v129, 0xffff0000, v198
	v_lshlrev_b32_e32 v130, 16, v199
	v_and_b32_e32 v131, 0xffff0000, v199
	v_pk_mul_f32 v[72:73], v[72:73], v[128:129]
	v_pk_mul_f32 v[74:75], v[74:75], v[130:131]
	s_waitcnt vmcnt(2)
	v_lshlrev_b32_e32 v128, 16, v200
	v_and_b32_e32 v129, 0xffff0000, v200
	v_lshlrev_b32_e32 v130, 16, v201
	v_and_b32_e32 v131, 0xffff0000, v201
	v_pk_mul_f32 v[12:13], v[12:13], v[128:129]
	v_pk_mul_f32 v[14:15], v[14:15], v[130:131]
	v_lshlrev_b32_e32 v128, 16, v202
	v_and_b32_e32 v129, 0xffff0000, v202
	v_lshlrev_b32_e32 v130, 16, v203
	v_and_b32_e32 v131, 0xffff0000, v203
	v_pk_mul_f32 v[8:9], v[8:9], v[128:129]
	v_pk_mul_f32 v[10:11], v[10:11], v[130:131]
	s_waitcnt vmcnt(1)
	v_lshlrev_b32_e32 v128, 16, v204
	v_and_b32_e32 v129, 0xffff0000, v204
	v_lshlrev_b32_e32 v130, 16, v205
	v_and_b32_e32 v131, 0xffff0000, v205
	v_pk_mul_f32 v[68:69], v[68:69], v[128:129]
	v_pk_mul_f32 v[70:71], v[70:71], v[130:131]
	v_lshlrev_b32_e32 v128, 16, v206
	v_and_b32_e32 v129, 0xffff0000, v206
	v_lshlrev_b32_e32 v130, 16, v207
	v_and_b32_e32 v131, 0xffff0000, v207
	v_pk_mul_f32 v[64:65], v[64:65], v[128:129]
	v_pk_mul_f32 v[66:67], v[66:67], v[130:131]
	s_waitcnt vmcnt(0)
	v_lshlrev_b32_e32 v128, 16, v208
	v_and_b32_e32 v129, 0xffff0000, v208
	v_lshlrev_b32_e32 v130, 16, v209
	v_and_b32_e32 v131, 0xffff0000, v209
	v_pk_mul_f32 v[4:5], v[4:5], v[128:129]
	v_pk_mul_f32 v[6:7], v[6:7], v[130:131]
	v_lshlrev_b32_e32 v128, 16, v210
	v_and_b32_e32 v129, 0xffff0000, v210
	v_lshlrev_b32_e32 v130, 16, v211
	v_and_b32_e32 v131, 0xffff0000, v211
	v_pk_mul_f32 v[0:1], v[0:1], v[128:129]
	v_pk_mul_f32 v[2:3], v[2:3], v[130:131]
	s_branch .LBB0_300
